# v33 + mixA gelu-gamma stage: both gamma groups (8 dwordx4) issued with the v loads into free VGPRs, counted vmcnt, bit-identical
# baseline (speedup 1.0000x reference)
; __device__ __forceinline__ float gelu_t(float x) { float u = 0.7978845608028654f * (x + 0.044715f * x * x * x); return x * __builtin_amdgcn_rcpf(1.f + __expf(-2.f * u)); }
; __device__ __forceinline__ void mixA_item(const Params& P, int layer, int idx, const bf16_t* z, bf16_t* y, char* lds) {
;     ...
;     const int s = tid >> 1, half = tid & 1;
;     const bf16_t* zr = z + (size_t)(tok0 + s) * LDZ + ZC_AV;
;     float ss = 0.f;
; #pragma unroll 4
;     for (int i = 0; i < 16; ++i) { float v[8]; unpack8(*(const u32x4*)(zr + half * 128 + i * 8), v);
; #pragma unroll
;       for (int e = 0; e < 8; ++e) { const float t = gelu_t(v[e]); ss += t * t; } }
;     ss += __shfl_xor(ss, 1);
;     const float rs = rsqrtf(ss * (1.f / 256.f) + 1e-6f);
.Lmixa_nj:
	s_cmpk_eq_i32 s38, 0x100
	v_lshlrev_b32_e32 v11, 16, v12
	v_mul_f32_e32 v20, 0x3d372713, v11
	v_mul_f32_e32 v20, v20, v11
	v_fma_f32 v20, v20, v11, v11
	v_mul_f32_e32 v20, 0x3f4c422a, v20
	v_mul_f32_e32 v20, -2.0, v20
	v_mul_f32_e32 v20, 0x3fb8aa3b, v20
	v_exp_f32_e32 v20, v20
	v_lshlrev_b32_e32 v21, 16, v13
	v_and_b32_e32 v24, 0xffff0000, v15
	v_add_f32_e32 v20, 1.0, v20
	v_rcp_f32_e32 v20, v20
	s_nop 0
	v_mul_f32_e32 v11, v20, v11
	v_and_b32_e32 v20, 0xffff0000, v12
	v_fmac_f32_e32 v10, v11, v11
	v_mul_f32_e32 v11, 0x3d372713, v20
	v_mul_f32_e32 v11, v11, v20
	v_mov_b32_e32 v12, v20
	v_fmac_f32_e32 v12, v11, v12
	v_mul_f32_e32 v11, 0x3f4c422a, v12
	v_mul_f32_e32 v11, -2.0, v11
	v_mul_f32_e32 v11, 0x3fb8aa3b, v11
	v_exp_f32_e32 v11, v11
	v_mov_b32_e32 v12, v21
	v_add_f32_e32 v11, 1.0, v11
	v_rcp_f32_e32 v22, v11
	v_mul_f32_e32 v11, 0x3d372713, v21
	v_mul_f32_e32 v11, v11, v21
	v_fmac_f32_e32 v12, v11, v12
	v_mul_f32_e32 v11, 0x3f4c422a, v12
	v_mul_f32_e32 v11, -2.0, v11
	v_mul_f32_e32 v11, 0x3fb8aa3b, v11
	v_exp_f32_e32 v11, v11
	s_nop 0
	v_add_f32_e32 v11, 1.0, v11
	v_rcp_f32_e32 v23, v11
	v_lshlrev_b32_e32 v11, 16, v14
	v_pk_mul_f32 v[20:21], v[22:23], v[20:21]
	s_nop 0
	v_pk_mul_f32 v[20:21], v[20:21], v[20:21]
	s_nop 0
	v_add_f32_e32 v10, v20, v10
	v_add_f32_e32 v20, v21, v10
	v_and_b32_e32 v10, 0xffff0000, v13
	v_mul_f32_e32 v12, 0x3d372713, v10
	v_mul_f32_e32 v12, v12, v10
	v_mov_b32_e32 v13, v10
	v_fmac_f32_e32 v13, v12, v13
	v_mul_f32_e32 v12, 0x3f4c422a, v13
	v_mul_f32_e32 v13, 0x3d372713, v11
	v_mul_f32_e32 v13, v13, v11
	v_mov_b32_e32 v21, v11
	v_fmac_f32_e32 v21, v13, v21
	v_mul_f32_e32 v13, 0x3f4c422a, v21
	v_mul_f32_e32 v12, -2.0, v12
	v_mul_f32_e32 v13, -2.0, v13
	v_mul_f32_e32 v12, 0x3fb8aa3b, v12
	v_mul_f32_e32 v13, 0x3fb8aa3b, v13
	v_exp_f32_e32 v12, v12
	v_exp_f32_e32 v13, v13
	v_add_f32_e32 v12, 1.0, v12
	v_add_f32_e32 v13, 1.0, v13
	v_rcp_f32_e32 v12, v12
	v_rcp_f32_e32 v13, v13
	s_nop 0
	v_pk_mul_f32 v[10:11], v[12:13], v[10:11]
	s_nop 0
	v_pk_mul_f32 v[10:11], v[10:11], v[10:11]
	s_nop 0
	v_add_f32_e32 v10, v10, v20
	v_add_f32_e32 v20, v11, v10
	v_and_b32_e32 v10, 0xffff0000, v14
	v_mul_f32_e32 v12, 0x3d372713, v10
	v_mul_f32_e32 v12, v12, v10
	v_mov_b32_e32 v13, v10
	v_lshlrev_b32_e32 v11, 16, v15
	v_fmac_f32_e32 v13, v12, v13
	v_mul_f32_e32 v12, 0x3f4c422a, v13
	v_mul_f32_e32 v13, 0x3d372713, v11
	v_mul_f32_e32 v13, v13, v11
	v_mov_b32_e32 v14, v11
	v_fmac_f32_e32 v14, v13, v14
	v_mul_f32_e32 v13, 0x3f4c422a, v14
	v_mul_f32_e32 v12, -2.0, v12
	v_mul_f32_e32 v13, -2.0, v13
	v_mul_f32_e32 v12, 0x3fb8aa3b, v12
	v_mul_f32_e32 v13, 0x3fb8aa3b, v13
	v_exp_f32_e32 v12, v12
	v_exp_f32_e32 v13, v13
	v_and_b32_e32 v15, 0xffff0000, v19
	v_add_f32_e32 v12, 1.0, v12
	v_add_f32_e32 v13, 1.0, v13
	v_rcp_f32_e32 v12, v12
	v_rcp_f32_e32 v13, v13
	s_nop 0
	v_pk_mul_f32 v[10:11], v[12:13], v[10:11]
	s_nop 0
	v_pk_mul_f32 v[10:11], v[10:11], v[10:11]
	s_nop 0
	v_add_f32_e32 v10, v10, v20
	v_add_f32_e32 v14, v11, v10
	v_mul_f32_e32 v10, 0x3d372713, v24
	v_mul_f32_e32 v10, v10, v24
	v_fma_f32 v10, v10, v24, v24
	v_mul_f32_e32 v10, 0x3f4c422a, v10
	v_mul_f32_e32 v10, -2.0, v10
	v_mul_f32_e32 v10, 0x3fb8aa3b, v10
	v_exp_f32_e32 v10, v10
	s_nop 0
	v_add_f32_e32 v10, 1.0, v10
	v_rcp_f32_e32 v10, v10
	s_nop 0
	v_mul_f32_e32 v10, v10, v24
	v_fmac_f32_e32 v14, v10, v10
	v_lshlrev_b32_e32 v10, 16, v16
	v_mul_f32_e32 v11, 0x3d372713, v10
	v_mul_f32_e32 v11, v11, v10
	v_fma_f32 v11, v11, v10, v10
	v_mul_f32_e32 v11, 0x3f4c422a, v11
	v_mul_f32_e32 v11, -2.0, v11
	v_mul_f32_e32 v11, 0x3fb8aa3b, v11
	v_exp_f32_e32 v11, v11
	s_nop 0
	v_add_f32_e32 v11, 1.0, v11
	v_rcp_f32_e32 v11, v11
	s_nop 0
	v_mul_f32_e32 v10, v11, v10
	v_fmac_f32_e32 v14, v10, v10
	v_and_b32_e32 v10, 0xffff0000, v16
	v_mul_f32_e32 v12, 0x3d372713, v10
	v_mul_f32_e32 v12, v12, v10
	v_mov_b32_e32 v13, v10
	v_lshlrev_b32_e32 v11, 16, v17
	v_fmac_f32_e32 v13, v12, v13
	v_mul_f32_e32 v12, 0x3f4c422a, v13
	v_mul_f32_e32 v13, 0x3d372713, v11
	v_mul_f32_e32 v13, v13, v11
	v_mov_b32_e32 v16, v11
	v_fmac_f32_e32 v16, v13, v16
	v_mul_f32_e32 v13, 0x3f4c422a, v16
	v_mul_f32_e32 v12, -2.0, v12
	v_mul_f32_e32 v13, -2.0, v13
	v_mul_f32_e32 v12, 0x3fb8aa3b, v12
	v_mul_f32_e32 v13, 0x3fb8aa3b, v13
	v_exp_f32_e32 v12, v12
	v_exp_f32_e32 v13, v13
	v_add_f32_e32 v12, 1.0, v12
	v_add_f32_e32 v13, 1.0, v13
	v_rcp_f32_e32 v12, v12
	v_rcp_f32_e32 v13, v13
	s_nop 0
	v_pk_mul_f32 v[10:11], v[12:13], v[10:11]
	s_nop 0
	v_pk_mul_f32 v[10:11], v[10:11], v[10:11]
	s_nop 0
	v_add_f32_e32 v10, v10, v14
	v_add_f32_e32 v14, v11, v10
	v_and_b32_e32 v10, 0xffff0000, v17
	v_mul_f32_e32 v12, 0x3d372713, v10
	v_mul_f32_e32 v12, v12, v10
	v_mov_b32_e32 v13, v10
	v_lshlrev_b32_e32 v11, 16, v18
	v_fmac_f32_e32 v13, v12, v13
	v_mul_f32_e32 v12, 0x3f4c422a, v13
	v_mul_f32_e32 v13, 0x3d372713, v11
	v_mul_f32_e32 v13, v13, v11
	v_mov_b32_e32 v16, v11
	v_fmac_f32_e32 v16, v13, v16
	v_mul_f32_e32 v13, 0x3f4c422a, v16
	v_mul_f32_e32 v12, -2.0, v12
	v_mul_f32_e32 v13, -2.0, v13
	v_mul_f32_e32 v12, 0x3fb8aa3b, v12
	v_mul_f32_e32 v13, 0x3fb8aa3b, v13
	v_exp_f32_e32 v12, v12
	v_exp_f32_e32 v13, v13
	v_add_f32_e32 v12, 1.0, v12
	v_add_f32_e32 v13, 1.0, v13
	v_rcp_f32_e32 v12, v12
	v_rcp_f32_e32 v13, v13
	s_nop 0
	v_pk_mul_f32 v[10:11], v[12:13], v[10:11]
	s_nop 0
	v_pk_mul_f32 v[10:11], v[10:11], v[10:11]
	s_nop 0
	v_add_f32_e32 v10, v10, v14
	v_add_f32_e32 v14, v11, v10
	v_and_b32_e32 v10, 0xffff0000, v18
	v_mul_f32_e32 v12, 0x3d372713, v10
	v_mul_f32_e32 v12, v12, v10
	v_mov_b32_e32 v13, v10
	v_lshlrev_b32_e32 v11, 16, v19
	v_fmac_f32_e32 v13, v12, v13
	v_mul_f32_e32 v12, 0x3f4c422a, v13
	v_mul_f32_e32 v13, 0x3d372713, v11
; __device__ __forceinline__ float gelu_t(float x) { float u = 0.7978845608028654f * (x + 0.044715f * x * x * x); return x * __builtin_amdgcn_rcpf(1.f + __expf(-2.f * u)); }
; __device__ __forceinline__ void mixA_item(const Params& P, int layer, int idx, const bf16_t* z, bf16_t* y, char* lds) {
;     ...
;     const int s = tid >> 1, half = tid & 1;
;     const bf16_t* zr = z + (size_t)(tok0 + s) * LDZ + ZC_AV;
;     float ss = 0.f;
; #pragma unroll 4
;     for (int i = 0; i < 16; ++i) { float v[8]; unpack8(*(const u32x4*)(zr + half * 128 + i * 8), v);
; #pragma unroll
;       for (int e = 0; e < 8; ++e) { const float t = gelu_t(v[e]); ss += t * t; } }
;     ss += __shfl_xor(ss, 1);
;     const float rs = rsqrtf(ss * (1.f / 256.f) + 1e-6f);
	v_mul_f32_e32 v13, v13, v11
	v_mov_b32_e32 v16, v11
	v_fmac_f32_e32 v16, v13, v16
	v_mul_f32_e32 v13, 0x3f4c422a, v16
	v_mul_f32_e32 v12, -2.0, v12
	v_mul_f32_e32 v13, -2.0, v13
	v_mul_f32_e32 v12, 0x3fb8aa3b, v12
	v_mul_f32_e32 v13, 0x3fb8aa3b, v13
	v_exp_f32_e32 v12, v12
	v_exp_f32_e32 v13, v13
	v_add_f32_e32 v12, 1.0, v12
	v_add_f32_e32 v13, 1.0, v13
	v_rcp_f32_e32 v12, v12
	v_rcp_f32_e32 v13, v13
	s_nop 0
	v_pk_mul_f32 v[10:11], v[12:13], v[10:11]
	s_nop 0
	v_pk_mul_f32 v[10:11], v[10:11], v[10:11]
	s_nop 0
	v_add_f32_e32 v10, v10, v14
	v_add_f32_e32 v14, v11, v10
	v_mul_f32_e32 v10, 0x3d372713, v15
	v_mul_f32_e32 v10, v10, v15
	v_fma_f32 v10, v10, v15, v15
	v_mul_f32_e32 v10, 0x3f4c422a, v10
	v_mul_f32_e32 v10, -2.0, v10
	v_mul_f32_e32 v10, 0x3fb8aa3b, v10
	v_exp_f32_e32 v10, v10
	s_nop 0
	v_add_f32_e32 v10, 1.0, v10
	v_rcp_f32_e32 v10, v10
	s_nop 0
	v_mul_f32_e32 v10, v10, v15
	v_fmac_f32_e32 v14, v10, v10
	v_lshlrev_b32_e32 v10, 16, v4
	v_mul_f32_e32 v11, 0x3d372713, v10
	v_mul_f32_e32 v11, v11, v10
	v_fma_f32 v11, v11, v10, v10
	v_mul_f32_e32 v11, 0x3f4c422a, v11
	v_mul_f32_e32 v11, -2.0, v11
	v_mul_f32_e32 v11, 0x3fb8aa3b, v11
	v_exp_f32_e32 v11, v11
	v_and_b32_e32 v15, 0xffff0000, v7
	v_add_f32_e32 v11, 1.0, v11
	v_rcp_f32_e32 v11, v11
	s_nop 0
	v_mul_f32_e32 v10, v11, v10
	v_fmac_f32_e32 v14, v10, v10
	v_and_b32_e32 v10, 0xffff0000, v4
	v_mul_f32_e32 v4, 0x3d372713, v10
	v_mul_f32_e32 v4, v4, v10
	v_mov_b32_e32 v12, v10
	v_fmac_f32_e32 v12, v4, v12
	v_mul_f32_e32 v4, 0x3f4c422a, v12
	v_mul_f32_e32 v4, -2.0, v4
	v_mul_f32_e32 v4, 0x3fb8aa3b, v4
	v_exp_f32_e32 v4, v4
	v_lshlrev_b32_e32 v11, 16, v5
	v_mov_b32_e32 v13, v11
	v_add_f32_e32 v4, 1.0, v4
	v_rcp_f32_e32 v12, v4
	v_mul_f32_e32 v4, 0x3d372713, v11
	v_mul_f32_e32 v4, v4, v11
	v_fmac_f32_e32 v13, v4, v13
	v_mul_f32_e32 v4, 0x3f4c422a, v13
	v_mul_f32_e32 v4, -2.0, v4
	v_mul_f32_e32 v4, 0x3fb8aa3b, v4
	v_exp_f32_e32 v4, v4
	s_nop 0
	v_add_f32_e32 v4, 1.0, v4
	v_rcp_f32_e32 v13, v4
	s_nop 0
	v_pk_mul_f32 v[10:11], v[12:13], v[10:11]
	s_nop 0
	v_pk_mul_f32 v[10:11], v[10:11], v[10:11]
	s_nop 0
	v_add_f32_e32 v4, v10, v14
	v_and_b32_e32 v10, 0xffff0000, v5
	v_add_f32_e32 v12, v11, v4
	v_mul_f32_e32 v4, 0x3d372713, v10
	v_mul_f32_e32 v4, v4, v10
	v_mov_b32_e32 v5, v10
	v_lshlrev_b32_e32 v11, 16, v6
	v_fmac_f32_e32 v5, v4, v5
	v_mul_f32_e32 v4, 0x3f4c422a, v5
	v_mul_f32_e32 v5, 0x3d372713, v11
	v_mul_f32_e32 v5, v5, v11
	v_mov_b32_e32 v13, v11
	v_fmac_f32_e32 v13, v5, v13
	v_mul_f32_e32 v5, 0x3f4c422a, v13
	v_mul_f32_e32 v4, -2.0, v4
	v_mul_f32_e32 v5, -2.0, v5
	v_mul_f32_e32 v4, 0x3fb8aa3b, v4
	v_mul_f32_e32 v5, 0x3fb8aa3b, v5
	v_exp_f32_e32 v4, v4
	v_exp_f32_e32 v5, v5
	v_add_f32_e32 v4, 1.0, v4
	v_add_f32_e32 v5, 1.0, v5
	v_rcp_f32_e32 v4, v4
	v_rcp_f32_e32 v5, v5
	s_nop 0
	v_pk_mul_f32 v[4:5], v[4:5], v[10:11]
	s_nop 0
	v_pk_mul_f32 v[4:5], v[4:5], v[4:5]
	s_nop 0
	v_add_f32_e32 v4, v4, v12
	v_add_f32_e32 v10, v5, v4
	v_and_b32_e32 v4, 0xffff0000, v6
	v_mul_f32_e32 v6, 0x3d372713, v4
	v_lshlrev_b32_e32 v5, 16, v7
	v_mul_f32_e32 v6, v6, v4
	v_mov_b32_e32 v7, v4
	v_fmac_f32_e32 v7, v6, v7
	v_mul_f32_e32 v6, 0x3f4c422a, v7
	v_mul_f32_e32 v7, 0x3d372713, v5
	v_mul_f32_e32 v7, v7, v5
	v_mov_b32_e32 v11, v5
	v_fmac_f32_e32 v11, v7, v11
	v_mul_f32_e32 v7, 0x3f4c422a, v11
	v_mul_f32_e32 v6, -2.0, v6
	v_mul_f32_e32 v7, -2.0, v7
	v_mul_f32_e32 v6, 0x3fb8aa3b, v6
	v_mul_f32_e32 v7, 0x3fb8aa3b, v7
	v_exp_f32_e32 v6, v6
	v_exp_f32_e32 v7, v7
	v_and_b32_e32 v11, 0xffff0000, v3
	v_add_f32_e32 v6, 1.0, v6
	v_add_f32_e32 v7, 1.0, v7
	v_rcp_f32_e32 v6, v6
	v_rcp_f32_e32 v7, v7
	s_nop 0
	v_pk_mul_f32 v[4:5], v[6:7], v[4:5]
	s_nop 0
	v_pk_mul_f32 v[4:5], v[4:5], v[4:5]
	s_nop 0
	v_add_f32_e32 v4, v4, v10
	v_add_f32_e32 v10, v5, v4
	v_mul_f32_e32 v4, 0x3d372713, v15
	v_mul_f32_e32 v4, v4, v15
	v_fma_f32 v4, v4, v15, v15
	v_mul_f32_e32 v4, 0x3f4c422a, v4
	v_mul_f32_e32 v4, -2.0, v4
	v_mul_f32_e32 v4, 0x3fb8aa3b, v4
	v_exp_f32_e32 v4, v4
	s_nop 0
	v_add_f32_e32 v4, 1.0, v4
	v_rcp_f32_e32 v4, v4
	s_nop 0
	v_mul_f32_e32 v4, v4, v15
	v_fmac_f32_e32 v10, v4, v4
	v_lshlrev_b32_e32 v4, 16, v0
	v_mul_f32_e32 v5, 0x3d372713, v4
	v_mul_f32_e32 v5, v5, v4
	v_fma_f32 v5, v5, v4, v4
	v_mul_f32_e32 v5, 0x3f4c422a, v5
	v_mul_f32_e32 v5, -2.0, v5
	v_mul_f32_e32 v5, 0x3fb8aa3b, v5
	v_exp_f32_e32 v5, v5
	s_nop 0
	v_add_f32_e32 v5, 1.0, v5
	v_rcp_f32_e32 v5, v5
	s_nop 0
	v_mul_f32_e32 v4, v5, v4
	v_fmac_f32_e32 v10, v4, v4
	v_and_b32_e32 v4, 0xffff0000, v0
	v_mul_f32_e32 v0, 0x3d372713, v4
	v_mul_f32_e32 v0, v0, v4
	v_mov_b32_e32 v6, v4
	v_fmac_f32_e32 v6, v0, v6
	v_mul_f32_e32 v0, 0x3f4c422a, v6
	v_mul_f32_e32 v0, -2.0, v0
	v_mul_f32_e32 v0, 0x3fb8aa3b, v0
	v_exp_f32_e32 v0, v0
	v_lshlrev_b32_e32 v5, 16, v1
	v_mov_b32_e32 v7, v5
	v_add_f32_e32 v0, 1.0, v0
	v_rcp_f32_e32 v6, v0
	v_mul_f32_e32 v0, 0x3d372713, v5
	v_mul_f32_e32 v0, v0, v5
	v_fmac_f32_e32 v7, v0, v7
	v_mul_f32_e32 v0, 0x3f4c422a, v7
	v_mul_f32_e32 v0, -2.0, v0
	v_mul_f32_e32 v0, 0x3fb8aa3b, v0
	v_exp_f32_e32 v0, v0
	s_nop 0
	v_add_f32_e32 v0, 1.0, v0
	v_rcp_f32_e32 v7, v0
	s_nop 0
	v_pk_mul_f32 v[4:5], v[6:7], v[4:5]
	s_nop 0
	v_pk_mul_f32 v[4:5], v[4:5], v[4:5]
	s_nop 0
	v_add_f32_e32 v0, v4, v10
	v_and_b32_e32 v4, 0xffff0000, v1
	v_add_f32_e32 v6, v5, v0
	v_mul_f32_e32 v0, 0x3d372713, v4
	v_mul_f32_e32 v0, v0, v4
	v_mov_b32_e32 v1, v4
	v_lshlrev_b32_e32 v5, 16, v2
	v_fmac_f32_e32 v1, v0, v1
	v_mul_f32_e32 v0, 0x3f4c422a, v1
	v_mul_f32_e32 v1, 0x3d372713, v5
	v_mul_f32_e32 v1, v1, v5
	v_mov_b32_e32 v7, v5
	v_fmac_f32_e32 v7, v1, v7
	v_mul_f32_e32 v1, 0x3f4c422a, v7
	v_mul_f32_e32 v0, -2.0, v0
	v_mul_f32_e32 v1, -2.0, v1
	v_mul_f32_e32 v0, 0x3fb8aa3b, v0
; __device__ __forceinline__ bf16_t f2bf(float f) { unsigned u = __float_as_uint(f); u += 0x7fffu + ((u >> 16) & 1u); return (bf16_t)(u >> 16); }
; __device__ __forceinline__ float gelu_t(float x) { float u = 0.7978845608028654f * (x + 0.044715f * x * x * x); return x * __builtin_amdgcn_rcpf(1.f + __expf(-2.f * u)); }
; __device__ __forceinline__ void mixA_item(const Params& P, int layer, int idx, const bf16_t* z, bf16_t* y, char* lds) {
;     ...
;     for (int i = 0; i < 16; ++i) { float v[8]; unpack8(*(const u32x4*)(zr + half * 128 + i * 8), v);
; #pragma unroll
;       for (int e = 0; e < 8; ++e) { const float t = gelu_t(v[e]); ss += t * t; } }
;     ss += __shfl_xor(ss, 1);
;     const float rs = rsqrtf(ss * (1.f / 256.f) + 1e-6f);
; #pragma unroll
;     for (int i = 0; i < 4; ++i) { float v[8]; unpack8(*(const u32x4*)(zr + g * 64 + half * 32 + i * 8), v);
; #pragma unroll
;       for (int e = 0; e < 8; ++e) { const int d = half * 32 + i * 8 + e; vT[d * 136 + s] = f2bf(gelu_t(v[e]) * rs * ng[g * 64 + d]); } }
	v_mul_f32_e32 v1, 0x3fb8aa3b, v1
	v_exp_f32_e32 v0, v0
	v_exp_f32_e32 v1, v1
	v_add_f32_e32 v0, 1.0, v0
	v_add_f32_e32 v1, 1.0, v1
	v_rcp_f32_e32 v0, v0
	v_rcp_f32_e32 v1, v1
	s_nop 0
	v_pk_mul_f32 v[0:1], v[0:1], v[4:5]
	s_nop 0
	v_pk_mul_f32 v[0:1], v[0:1], v[0:1]
	s_nop 0
	v_add_f32_e32 v0, v0, v6
	v_add_f32_e32 v4, v1, v0
	v_and_b32_e32 v0, 0xffff0000, v2
	v_mul_f32_e32 v2, 0x3d372713, v0
	v_lshlrev_b32_e32 v1, 16, v3
	v_mul_f32_e32 v2, v2, v0
	v_mov_b32_e32 v3, v0
	v_fmac_f32_e32 v3, v2, v3
	v_mul_f32_e32 v2, 0x3f4c422a, v3
	v_mul_f32_e32 v3, 0x3d372713, v1
	v_mul_f32_e32 v3, v3, v1
	v_mov_b32_e32 v5, v1
	v_fmac_f32_e32 v5, v3, v5
	v_mul_f32_e32 v3, 0x3f4c422a, v5
	v_mul_f32_e32 v2, -2.0, v2
	v_mul_f32_e32 v3, -2.0, v3
	v_mul_f32_e32 v2, 0x3fb8aa3b, v2
	v_mul_f32_e32 v3, 0x3fb8aa3b, v3
	v_exp_f32_e32 v2, v2
	v_exp_f32_e32 v3, v3
	v_add_f32_e32 v2, 1.0, v2
	v_add_f32_e32 v3, 1.0, v3
	v_rcp_f32_e32 v2, v2
	v_rcp_f32_e32 v3, v3
	s_nop 0
	v_pk_mul_f32 v[0:1], v[2:3], v[0:1]
	s_nop 0
	v_pk_mul_f32 v[0:1], v[0:1], v[0:1]
	s_nop 0
	v_add_f32_e32 v0, v0, v4
	v_add_f32_e32 v10, v1, v0
	v_mul_f32_e32 v0, 0x3d372713, v11
	v_mul_f32_e32 v0, v0, v11
	v_fma_f32 v0, v0, v11, v11
	v_mul_f32_e32 v0, 0x3f4c422a, v0
	v_mul_f32_e32 v0, -2.0, v0
	v_mul_f32_e32 v0, 0x3fb8aa3b, v0
	v_exp_f32_e32 v0, v0
	s_nop 0
	v_add_f32_e32 v0, 1.0, v0
	v_rcp_f32_e32 v0, v0
	s_nop 0
	v_mul_f32_e32 v0, v0, v11
	v_fmac_f32_e32 v10, v0, v0
	s_cbranch_scc0 .LBB0_549
	v_and_b32_e32 v0, 3, v42
	v_lshl_add_u32 v176, v0, 15, s17
	v_lshlrev_b32_e32 v0, 5, v43
	v_and_b32_e32 v36, 0xffffff80, v0
	v_or_b32_e32 v2, v29, v36
	v_mov_b64_e32 v[0:1], s[84:85]
	v_cmp_lt_i32_e32 vcc, v224, v218
	v_mad_i64_i32 v[0:1], s[30:31], v2, s43, v[0:1]
	s_nop 0
	v_cndmask_b32_e32 v2, v212, v224, vcc
	v_lshlrev_b32_e32 v2, 2, v2
	ds_bpermute_b32 v2, v2, v10
	s_mov_b32 s30, 0x800000
	v_and_b32_e32 v37, 3, v43
	v_lshlrev_b32_e32 v32, 6, v37
	v_lshlrev_b32_e32 v44, 5, v30
	s_waitcnt lgkmcnt(0)
	v_add_f32_e32 v2, v10, v2
	v_fmamk_f32 v2, v2, 0x3b800000, v178
	v_cmp_gt_f32_e32 vcc, s30, v2
	v_mul_f32_e32 v3, 0x4b800000, v2
	v_lshlrev_b32_e32 v29, 1, v29
	v_cndmask_b32_e32 v2, v2, v3, vcc
	v_rsq_f32_e32 v2, v2
	v_and_b32_e32 v38, 15, v28
	v_lshrrev_b32_sdwa v33, v232, v28 dst_sel:DWORD dst_unused:UNUSED_PAD src0_sel:DWORD src1_sel:BYTE_0
	v_readlane_b32 s30, v254, 45
	v_mul_f32_e32 v3, 0x45800000, v2
	v_cndmask_b32_e32 v31, v2, v3, vcc
	v_lshlrev_b32_e32 v2, 7, v37
	v_mov_b32_e32 v3, v177
	v_lshl_add_u64 v[0:1], v[0:1], 0, v[2:3]
	v_lshlrev_b32_e32 v2, 6, v30
	v_lshl_add_u64 v[8:9], v[0:1], 0, v[2:3]
	global_load_dwordx4 v[0:3], v[8:9], off offset:560
	global_load_dwordx4 v[4:7], v[8:9], off offset:544
	global_load_dwordx4 v[16:19], v[8:9], off offset:528
	s_nop 0
	global_load_dwordx4 v[8:11], v[8:9], off offset:512
	v_or_b32_e32 v34, v44, v32
	v_lshlrev_b32_e32 v34, 2, v34
	global_load_dwordx4 v[84:87], v34, s[34:35] offset:48
	global_load_dwordx4 v[88:91], v34, s[34:35] offset:32
	global_load_dwordx4 v[92:95], v34, s[34:35] offset:16
	global_load_dwordx4 v[96:99], v34, s[34:35]
	global_load_dwordx4 v[50:53], v34, s[34:35] offset:112
	global_load_dwordx4 v[54:57], v34, s[34:35] offset:96
	global_load_dwordx4 v[62:65], v34, s[34:35] offset:80
	global_load_dwordx4 v[66:69], v34, s[34:35] offset:64
	v_mul_u32_u24_e32 v30, 0x2200, v30
	v_add3_u32 v30, v60, v30, v29
	v_readlane_b32 s31, v254, 46
	s_movk_i32 s38, 0x1000
	s_waitcnt vmcnt(8)
	v_lshlrev_b32_e32 v12, 16, v8
	v_and_b32_e32 v45, 0xffff0000, v8
	v_mul_f32_e32 v8, 0x3d372713, v12
	v_mul_f32_e32 v8, v8, v12
	v_fma_f32 v8, v8, v12, v12
	v_mul_f32_e32 v8, 0x3f4c422a, v8
	v_mul_f32_e32 v8, -2.0, v8
	v_mul_f32_e32 v8, 0x3fb8aa3b, v8
	v_exp_f32_e32 v8, v8
	v_lshlrev_b32_e32 v46, 16, v9
	v_and_b32_e32 v47, 0xffff0000, v9
	v_lshlrev_b32_e32 v48, 16, v10
	v_add_f32_e32 v8, 1.0, v8
	v_rcp_f32_e32 v8, v8
	v_and_b32_e32 v41, 0xffff0000, v10
	v_lshlrev_b32_e32 v40, 16, v11
	v_and_b32_e32 v35, 0xffff0000, v11
	v_mul_f32_e32 v8, v8, v12
	v_mul_f32_e32 v49, v31, v8
	v_or_b32_e32 v8, v44, v32
	v_lshlrev_b32_e32 v34, 2, v8
	s_waitcnt vmcnt(4)
	v_mov_b64_e32 v[8:9], v[84:85]
	v_mov_b64_e32 v[10:11], v[86:87]
	v_mov_b64_e32 v[12:13], v[88:89]
	v_mov_b64_e32 v[14:15], v[90:91]
	v_mov_b64_e32 v[20:21], v[92:93]
	v_mov_b64_e32 v[22:23], v[94:95]
	v_mov_b64_e32 v[24:25], v[96:97]
	v_mov_b64_e32 v[26:27], v[98:99]
	v_mul_f32_e32 v24, v24, v49
	v_bfe_u32 v49, v24, 16, 1
	v_add3_u32 v24, v24, v49, s42
	ds_write_b16_d16_hi v30, v24
	v_mul_f32_e32 v30, 0x3d372713, v45
	v_mul_f32_e32 v30, v30, v45
	v_fma_f32 v30, v30, v45, v45
	v_mul_f32_e32 v30, 0x3f4c422a, v30
	v_mul_f32_e32 v30, -2.0, v30
	v_mul_f32_e32 v30, 0x3fb8aa3b, v30
	v_exp_f32_e32 v30, v30
	v_or_b32_e32 v24, 1, v44
	v_mul_u32_u24_e32 v24, 0x110, v24
	v_add3_u32 v24, v60, v24, v29
	v_add_f32_e32 v30, 1.0, v30
	v_rcp_f32_e32 v30, v30
	v_add_u32_e32 v44, 1, v33
	v_mul_f32_e32 v30, v30, v45
	v_mul_f32_e32 v30, v31, v30
	v_mul_f32_e32 v25, v25, v30
	v_bfe_u32 v30, v25, 16, 1
	v_add3_u32 v25, v25, v30, s42
	ds_write_b16_d16_hi v24, v25
	v_mul_f32_e32 v25, 0x3d372713, v46
	v_mul_f32_e32 v25, v25, v46
	v_fma_f32 v25, v25, v46, v46
	v_mul_f32_e32 v25, 0x3f4c422a, v25
	v_mul_f32_e32 v25, -2.0, v25
	v_mul_f32_e32 v25, 0x3fb8aa3b, v25
	v_exp_f32_e32 v25, v25
	s_nop 0
	v_add_f32_e32 v25, 1.0, v25
	v_rcp_f32_e32 v25, v25
	s_nop 0
	v_mul_f32_e32 v25, v25, v46
	v_mul_f32_e32 v25, v31, v25
	v_mul_f32_e32 v25, v26, v25
	v_bfe_u32 v26, v25, 16, 1
	v_add3_u32 v25, v25, v26, s42
	ds_write_b16_d16_hi v24, v25 offset:272
	v_mul_f32_e32 v25, 0x3d372713, v47
	v_mul_f32_e32 v25, v25, v47
	v_fma_f32 v25, v25, v47, v47
	v_mul_f32_e32 v25, 0x3f4c422a, v25
; __device__ __forceinline__ bf16_t f2bf(float f) { unsigned u = __float_as_uint(f); u += 0x7fffu + ((u >> 16) & 1u); return (bf16_t)(u >> 16); }
; __device__ __forceinline__ float gelu_t(float x) { float u = 0.7978845608028654f * (x + 0.044715f * x * x * x); return x * __builtin_amdgcn_rcpf(1.f + __expf(-2.f * u)); }
; __device__ __forceinline__ void mixA_item(const Params& P, int layer, int idx, const bf16_t* z, bf16_t* y, char* lds) {
;     ...
;     for (int i = 0; i < 4; ++i) { float v[8]; unpack8(*(const u32x4*)(zr + g * 64 + half * 32 + i * 8), v);
; #pragma unroll
;       for (int e = 0; e < 8; ++e) { const int d = half * 32 + i * 8 + e; vT[d * 136 + s] = f2bf(gelu_t(v[e]) * rs * ng[g * 64 + d]); } }
	v_mul_f32_e32 v25, -2.0, v25
	v_mul_f32_e32 v25, 0x3fb8aa3b, v25
	v_exp_f32_e32 v25, v25
	s_nop 0
	v_add_f32_e32 v25, 1.0, v25
	v_rcp_f32_e32 v25, v25
	s_nop 0
	v_mul_f32_e32 v25, v25, v47
	v_mul_f32_e32 v25, v31, v25
	v_mul_f32_e32 v25, v27, v25
	v_bfe_u32 v26, v25, 16, 1
	v_add3_u32 v25, v25, v26, s42
	ds_write_b16_d16_hi v24, v25 offset:544
	v_mul_f32_e32 v25, 0x3d372713, v48
	v_mul_f32_e32 v25, v25, v48
	v_fma_f32 v25, v25, v48, v48
	v_mul_f32_e32 v25, 0x3f4c422a, v25
	v_mul_f32_e32 v25, -2.0, v25
	v_mul_f32_e32 v25, 0x3fb8aa3b, v25
	v_exp_f32_e32 v25, v25
	v_and_b32_e32 v27, 0xffff0000, v4
	v_lshlrev_b32_e32 v26, 16, v5
	v_add_f32_e32 v25, 1.0, v25
	v_rcp_f32_e32 v25, v25
	s_nop 0
	v_mul_f32_e32 v25, v25, v48
	v_mul_f32_e32 v25, v31, v25
	v_mul_f32_e32 v20, v20, v25
	v_bfe_u32 v25, v20, 16, 1
	v_add3_u32 v20, v20, v25, s42
	ds_write_b16_d16_hi v24, v20 offset:816
	v_mul_f32_e32 v20, 0x3d372713, v41
	v_mul_f32_e32 v20, v20, v41
	v_fma_f32 v20, v20, v41, v41
	v_mul_f32_e32 v20, 0x3f4c422a, v20
	v_mul_f32_e32 v20, -2.0, v20
	v_mul_f32_e32 v20, 0x3fb8aa3b, v20
	v_exp_f32_e32 v20, v20
	s_nop 0
	v_add_f32_e32 v20, 1.0, v20
	v_rcp_f32_e32 v20, v20
	s_nop 0
	v_mul_f32_e32 v20, v20, v41
	v_mul_f32_e32 v20, v31, v20
	v_mul_f32_e32 v20, v21, v20
	v_bfe_u32 v21, v20, 16, 1
	v_add3_u32 v20, v20, v21, s42
	ds_write_b16_d16_hi v24, v20 offset:1088
	v_mul_f32_e32 v20, 0x3d372713, v40
	v_mul_f32_e32 v20, v20, v40
	v_fma_f32 v20, v20, v40, v40
	v_mul_f32_e32 v20, 0x3f4c422a, v20
	v_mul_f32_e32 v20, -2.0, v20
	v_mul_f32_e32 v20, 0x3fb8aa3b, v20
	v_exp_f32_e32 v20, v20
	s_nop 0
	v_add_f32_e32 v20, 1.0, v20
	v_rcp_f32_e32 v20, v20
	s_nop 0
	v_mul_f32_e32 v20, v20, v40
	v_mul_f32_e32 v20, v31, v20
	v_mul_f32_e32 v20, v22, v20
	v_bfe_u32 v21, v20, 16, 1
	v_add3_u32 v20, v20, v21, s42
	ds_write_b16_d16_hi v24, v20 offset:1360
	v_mul_f32_e32 v20, 0x3d372713, v35
	v_mul_f32_e32 v20, v20, v35
	v_fma_f32 v20, v20, v35, v35
	v_mul_f32_e32 v20, 0x3f4c422a, v20
	v_mul_f32_e32 v20, -2.0, v20
	v_mul_f32_e32 v20, 0x3fb8aa3b, v20
	v_exp_f32_e32 v20, v20
	v_lshlrev_b32_e32 v22, 16, v18
	v_and_b32_e32 v18, 0xffff0000, v18
	v_bfe_u32 v40, v28, 4, 2
	v_add_f32_e32 v20, 1.0, v20
	v_rcp_f32_e32 v20, v20
	s_nop 0
	v_mul_f32_e32 v20, v20, v35
	v_mul_f32_e32 v20, v31, v20
	v_mul_f32_e32 v20, v20, v23
	v_bfe_u32 v21, v20, 16, 1
	v_add3_u32 v20, v20, v21, s42
	ds_write_b16_d16_hi v24, v20 offset:1632
	v_lshlrev_b32_e32 v20, 16, v16
	v_mul_f32_e32 v25, 0x3d372713, v20
	v_mul_f32_e32 v25, v25, v20
	v_fma_f32 v25, v25, v20, v20
	v_mul_f32_e32 v25, 0x3f4c422a, v25
	v_mul_f32_e32 v25, -2.0, v25
	v_mul_f32_e32 v25, 0x3fb8aa3b, v25
	v_exp_f32_e32 v25, v25
	v_and_b32_e32 v16, 0xffff0000, v16
	v_lshlrev_b32_e32 v21, 16, v17
	v_and_b32_e32 v17, 0xffff0000, v17
	v_add_f32_e32 v25, 1.0, v25
	v_rcp_f32_e32 v25, v25
	v_lshlrev_b32_e32 v23, 16, v19
	v_and_b32_e32 v19, 0xffff0000, v19
	v_mul_f32_e32 v20, v25, v20
	v_mul_f32_e32 v20, v31, v20
	v_mul_f32_e32 v12, v12, v20
	v_bfe_u32 v20, v12, 16, 1
	v_add3_u32 v12, v12, v20, s42
	ds_write_b16_d16_hi v24, v12 offset:1904
	v_mul_f32_e32 v12, 0x3d372713, v16
	v_mul_f32_e32 v12, v12, v16
	v_fma_f32 v12, v12, v16, v16
	v_mul_f32_e32 v12, 0x3f4c422a, v12
	v_mul_f32_e32 v12, -2.0, v12
	v_mul_f32_e32 v12, 0x3fb8aa3b, v12
	v_exp_f32_e32 v12, v12
	v_and_b32_e32 v25, 0xffff0000, v5
	v_and_b32_e32 v20, 0xffff0000, v7
	v_add_f32_e32 v12, 1.0, v12
	v_rcp_f32_e32 v12, v12
	s_nop 0
	v_mul_f32_e32 v12, v12, v16
	v_mul_f32_e32 v12, v31, v12
	v_mul_f32_e32 v12, v13, v12
	v_bfe_u32 v13, v12, 16, 1
	v_add3_u32 v12, v12, v13, s42
	ds_write_b16_d16_hi v24, v12 offset:2176
	v_mul_f32_e32 v12, 0x3d372713, v21
	v_mul_f32_e32 v12, v12, v21
	v_fma_f32 v12, v12, v21, v21
	v_mul_f32_e32 v12, 0x3f4c422a, v12
	v_mul_f32_e32 v12, -2.0, v12
	v_mul_f32_e32 v12, 0x3fb8aa3b, v12
	v_exp_f32_e32 v12, v12
	s_nop 0
	v_add_f32_e32 v12, 1.0, v12
	v_rcp_f32_e32 v12, v12
	s_nop 0
	v_mul_f32_e32 v12, v12, v21
	v_mul_f32_e32 v12, v31, v12
	v_mul_f32_e32 v12, v14, v12
	v_bfe_u32 v13, v12, 16, 1
	v_add3_u32 v12, v12, v13, s42
	ds_write_b16_d16_hi v24, v12 offset:2448
	v_mul_f32_e32 v12, 0x3d372713, v17
	v_mul_f32_e32 v12, v12, v17
	v_fma_f32 v12, v12, v17, v17
	v_mul_f32_e32 v12, 0x3f4c422a, v12
	v_mul_f32_e32 v12, -2.0, v12
	v_mul_f32_e32 v12, 0x3fb8aa3b, v12
	v_exp_f32_e32 v12, v12
	v_lshlrev_b32_e32 v21, 16, v7
	v_add_f32_e32 v12, 1.0, v12
	v_rcp_f32_e32 v12, v12
	s_nop 0
	v_mul_f32_e32 v12, v12, v17
	v_mul_f32_e32 v12, v31, v12
	v_mul_f32_e32 v12, v15, v12
	v_bfe_u32 v13, v12, 16, 1
	v_add3_u32 v12, v12, v13, s42
	ds_write_b16_d16_hi v24, v12 offset:2720
	v_mul_f32_e32 v12, 0x3d372713, v22
	v_mul_f32_e32 v12, v12, v22
	v_fma_f32 v12, v12, v22, v22
	v_mul_f32_e32 v12, 0x3f4c422a, v12
	v_mul_f32_e32 v12, -2.0, v12
	v_mul_f32_e32 v12, 0x3fb8aa3b, v12
	v_exp_f32_e32 v12, v12
	s_nop 0
	v_add_f32_e32 v12, 1.0, v12
	v_rcp_f32_e32 v12, v12
	s_nop 0
	v_mul_f32_e32 v12, v12, v22
	v_mul_f32_e32 v12, v31, v12
	v_mul_f32_e32 v8, v8, v12
	v_bfe_u32 v12, v8, 16, 1
	v_add3_u32 v8, v8, v12, s42
	ds_write_b16_d16_hi v24, v8 offset:2992
	v_mul_f32_e32 v8, 0x3d372713, v18
	v_mul_f32_e32 v8, v8, v18
	v_fma_f32 v8, v8, v18, v18
	v_mul_f32_e32 v8, 0x3f4c422a, v8
	v_mul_f32_e32 v8, -2.0, v8
	v_mul_f32_e32 v8, 0x3fb8aa3b, v8
	v_exp_f32_e32 v8, v8
	v_and_b32_e32 v22, 0xffff0000, v6
	v_add_f32_e32 v8, 1.0, v8
	v_rcp_f32_e32 v8, v8
	s_nop 0
	v_mul_f32_e32 v8, v8, v18
	v_mul_f32_e32 v8, v31, v8
	v_mul_f32_e32 v8, v9, v8
	v_bfe_u32 v9, v8, 16, 1
	v_add3_u32 v8, v8, v9, s42
	ds_write_b16_d16_hi v24, v8 offset:3264
	v_mul_f32_e32 v8, 0x3d372713, v23
	v_mul_f32_e32 v8, v8, v23
	v_fma_f32 v8, v8, v23, v23
	v_mul_f32_e32 v8, 0x3f4c422a, v8
	v_mul_f32_e32 v8, -2.0, v8
	v_mul_f32_e32 v8, 0x3fb8aa3b, v8
	v_exp_f32_e32 v8, v8
	s_nop 0
	v_add_f32_e32 v8, 1.0, v8
	v_rcp_f32_e32 v8, v8
	s_nop 0
	v_mul_f32_e32 v8, v8, v23
	v_mul_f32_e32 v8, v31, v8
	v_mul_f32_e32 v8, v10, v8
	v_bfe_u32 v9, v8, 16, 1
	v_add3_u32 v8, v8, v9, s42
	ds_write_b16_d16_hi v24, v8 offset:3536
	v_mul_f32_e32 v8, 0x3d372713, v19
	v_mul_f32_e32 v8, v8, v19
	v_fma_f32 v8, v8, v19, v19
	v_mul_f32_e32 v8, 0x3f4c422a, v8
	v_mul_f32_e32 v8, -2.0, v8
	v_mul_f32_e32 v8, 0x3fb8aa3b, v8
	v_exp_f32_e32 v8, v8
	v_lshlrev_b32_e32 v23, 16, v6
	v_add_f32_e32 v8, 1.0, v8
	v_rcp_f32_e32 v8, v8
	s_nop 0
	v_mul_f32_e32 v8, v8, v19
	v_mul_f32_e32 v8, v31, v8
	v_mul_f32_e32 v8, v8, v11
	v_bfe_u32 v9, v8, 16, 1
	v_add3_u32 v8, v8, v9, s42
	ds_write_b16_d16_hi v24, v8 offset:3808
	v_lshlrev_b32_e32 v8, 16, v4
	v_mul_f32_e32 v4, 0x3d372713, v8
	v_mul_f32_e32 v4, v4, v8
	v_fma_f32 v4, v4, v8, v8
	v_mul_f32_e32 v4, 0x3f4c422a, v4
	v_mul_f32_e32 v4, -2.0, v4
	v_mul_f32_e32 v4, 0x3fb8aa3b, v4
	v_exp_f32_e32 v4, v4
	s_nop 0
	v_add_f32_e32 v4, 1.0, v4
	v_rcp_f32_e32 v4, v4
	s_nop 0
	v_mul_f32_e32 v4, v4, v8
	v_mul_f32_e32 v29, v31, v4
	s_waitcnt vmcnt(0)
; __device__ __forceinline__ bf16_t f2bf(float f) { unsigned u = __float_as_uint(f); u += 0x7fffu + ((u >> 16) & 1u); return (bf16_t)(u >> 16); }
; __device__ __forceinline__ float gelu_t(float x) { float u = 0.7978845608028654f * (x + 0.044715f * x * x * x); return x * __builtin_amdgcn_rcpf(1.f + __expf(-2.f * u)); }
; __device__ __forceinline__ void mixA_item(const Params& P, int layer, int idx, const bf16_t* z, bf16_t* y, char* lds) {
;     ...
;     for (int i = 0; i < 4; ++i) { float v[8]; unpack8(*(const u32x4*)(zr + g * 64 + half * 32 + i * 8), v);
; #pragma unroll
;       for (int e = 0; e < 8; ++e) { const int d = half * 32 + i * 8 + e; vT[d * 136 + s] = f2bf(gelu_t(v[e]) * rs * ng[g * 64 + d]); } }
	v_mov_b64_e32 v[4:5], v[50:51]
	v_mov_b64_e32 v[6:7], v[52:53]
	v_mov_b64_e32 v[8:9], v[54:55]
	v_mov_b64_e32 v[10:11], v[56:57]
	v_mov_b64_e32 v[12:13], v[62:63]
	v_mov_b64_e32 v[14:15], v[64:65]
	v_mov_b64_e32 v[16:17], v[66:67]
	v_mov_b64_e32 v[18:19], v[68:69]
	v_mul_f32_e32 v16, v16, v29
	v_bfe_u32 v29, v16, 16, 1
	v_add3_u32 v16, v16, v29, s42
	ds_write_b16_d16_hi v24, v16 offset:4080
	v_mul_f32_e32 v16, 0x3d372713, v27
	v_mul_f32_e32 v16, v16, v27
	v_fma_f32 v16, v16, v27, v27
	v_mul_f32_e32 v16, 0x3f4c422a, v16
	v_mul_f32_e32 v16, -2.0, v16
	v_mul_f32_e32 v16, 0x3fb8aa3b, v16
	v_exp_f32_e32 v16, v16
	s_nop 0
	v_add_f32_e32 v16, 1.0, v16
	v_rcp_f32_e32 v16, v16
	s_nop 0
	v_mul_f32_e32 v16, v16, v27
	v_mul_f32_e32 v16, v31, v16
	v_mul_f32_e32 v16, v17, v16
	v_bfe_u32 v17, v16, 16, 1
	v_add3_u32 v16, v16, v17, s42
	ds_write_b16_d16_hi v24, v16 offset:4352
	v_mul_f32_e32 v16, 0x3d372713, v26
	v_mul_f32_e32 v16, v16, v26
	v_fma_f32 v16, v16, v26, v26
	v_mul_f32_e32 v16, 0x3f4c422a, v16
	v_mul_f32_e32 v16, -2.0, v16
	v_mul_f32_e32 v16, 0x3fb8aa3b, v16
	v_exp_f32_e32 v16, v16
	s_nop 0
	v_add_f32_e32 v16, 1.0, v16
	v_rcp_f32_e32 v16, v16
	s_nop 0
	v_mul_f32_e32 v16, v16, v26
	v_mul_f32_e32 v16, v31, v16
	v_mul_f32_e32 v16, v18, v16
	v_bfe_u32 v17, v16, 16, 1
	v_add3_u32 v16, v16, v17, s42
	ds_write_b16_d16_hi v24, v16 offset:4624
	v_mul_f32_e32 v16, 0x3d372713, v25
	v_mul_f32_e32 v16, v16, v25
	v_fma_f32 v16, v16, v25, v25
	v_mul_f32_e32 v16, 0x3f4c422a, v16
	v_mul_f32_e32 v16, -2.0, v16
	v_mul_f32_e32 v16, 0x3fb8aa3b, v16
	v_exp_f32_e32 v16, v16
	s_nop 0
	v_add_f32_e32 v16, 1.0, v16
	v_rcp_f32_e32 v16, v16
	s_nop 0
	v_mul_f32_e32 v16, v16, v25
	v_mul_f32_e32 v16, v31, v16
	v_mul_f32_e32 v16, v19, v16
	v_bfe_u32 v17, v16, 16, 1
	v_add3_u32 v16, v16, v17, s42
	ds_write_b16_d16_hi v24, v16 offset:4896
	v_mul_f32_e32 v16, 0x3d372713, v23
	v_mul_f32_e32 v16, v16, v23
	v_fma_f32 v16, v16, v23, v23
	v_mul_f32_e32 v16, 0x3f4c422a, v16
	v_mul_f32_e32 v16, -2.0, v16
	v_mul_f32_e32 v16, 0x3fb8aa3b, v16
	v_exp_f32_e32 v16, v16
	s_nop 0
	v_add_f32_e32 v16, 1.0, v16
	v_rcp_f32_e32 v16, v16
	s_nop 0
	v_mul_f32_e32 v16, v16, v23
	v_mul_f32_e32 v16, v31, v16
	v_mul_f32_e32 v12, v12, v16
	v_bfe_u32 v16, v12, 16, 1
	v_add3_u32 v12, v12, v16, s42
	ds_write_b16_d16_hi v24, v12 offset:5168
	v_mul_f32_e32 v12, 0x3d372713, v22
	v_mul_f32_e32 v12, v12, v22
	v_fma_f32 v12, v12, v22, v22
	v_mul_f32_e32 v12, 0x3f4c422a, v12
	v_mul_f32_e32 v12, -2.0, v12
	v_mul_f32_e32 v12, 0x3fb8aa3b, v12
	v_exp_f32_e32 v12, v12
	s_nop 0
	v_add_f32_e32 v12, 1.0, v12
	v_rcp_f32_e32 v12, v12
	s_nop 0
	v_mul_f32_e32 v12, v12, v22
	v_mul_f32_e32 v12, v31, v12
	v_mul_f32_e32 v12, v13, v12
	v_bfe_u32 v13, v12, 16, 1
	v_add3_u32 v12, v12, v13, s42
	ds_write_b16_d16_hi v24, v12 offset:5440
	v_mul_f32_e32 v12, 0x3d372713, v21
	v_mul_f32_e32 v12, v12, v21
	v_fma_f32 v12, v12, v21, v21
	v_mul_f32_e32 v12, 0x3f4c422a, v12
	v_mul_f32_e32 v12, -2.0, v12
	v_mul_f32_e32 v12, 0x3fb8aa3b, v12
	v_exp_f32_e32 v12, v12
	s_nop 0
	v_add_f32_e32 v12, 1.0, v12
	v_rcp_f32_e32 v12, v12
	s_nop 0
	v_mul_f32_e32 v12, v12, v21
	v_mul_f32_e32 v12, v31, v12
	v_mul_f32_e32 v12, v14, v12
	v_bfe_u32 v13, v12, 16, 1
	v_add3_u32 v12, v12, v13, s42
	ds_write_b16_d16_hi v24, v12 offset:5712
	v_mul_f32_e32 v12, 0x3d372713, v20
	v_mul_f32_e32 v12, v12, v20
	v_fma_f32 v12, v12, v20, v20
	v_mul_f32_e32 v12, 0x3f4c422a, v12
	v_mul_f32_e32 v12, -2.0, v12
	v_mul_f32_e32 v12, 0x3fb8aa3b, v12
	v_exp_f32_e32 v12, v12
	v_lshlrev_b32_e32 v14, 16, v2
	v_and_b32_e32 v2, 0xffff0000, v2
	v_add_f32_e32 v12, 1.0, v12
	v_rcp_f32_e32 v12, v12
	s_nop 0
	v_mul_f32_e32 v12, v12, v20
	v_mul_f32_e32 v12, v31, v12
	v_mul_f32_e32 v12, v12, v15
	v_bfe_u32 v13, v12, 16, 1
	v_add3_u32 v12, v12, v13, s42
	ds_write_b16_d16_hi v24, v12 offset:5984
	v_lshlrev_b32_e32 v12, 16, v0
	v_mul_f32_e32 v16, 0x3d372713, v12
	v_mul_f32_e32 v16, v16, v12
	v_fma_f32 v16, v16, v12, v12
	v_mul_f32_e32 v16, 0x3f4c422a, v16
	v_mul_f32_e32 v16, -2.0, v16
	v_mul_f32_e32 v16, 0x3fb8aa3b, v16
	v_exp_f32_e32 v16, v16
	v_and_b32_e32 v0, 0xffff0000, v0
	v_lshlrev_b32_e32 v13, 16, v1
	v_and_b32_e32 v1, 0xffff0000, v1
	v_add_f32_e32 v16, 1.0, v16
	v_rcp_f32_e32 v16, v16
	v_lshlrev_b32_e32 v15, 16, v3
	v_and_b32_e32 v3, 0xffff0000, v3
	v_mul_f32_e32 v12, v16, v12
	v_mul_f32_e32 v12, v31, v12
; __device__ __forceinline__ bf16_t f2bf(float f) { unsigned u = __float_as_uint(f); u += 0x7fffu + ((u >> 16) & 1u); return (bf16_t)(u >> 16); }
; __device__ __forceinline__ float gelu_t(float x) { float u = 0.7978845608028654f * (x + 0.044715f * x * x * x); return x * __builtin_amdgcn_rcpf(1.f + __expf(-2.f * u)); }
; __device__ __forceinline__ void mixA_item(const Params& P, int layer, int idx, const bf16_t* z, bf16_t* y, char* lds) {
;     ...
;     for (int i = 0; i < 4; ++i) { float v[8]; unpack8(*(const u32x4*)(zr + g * 64 + half * 32 + i * 8), v);
; #pragma unroll
;       for (int e = 0; e < 8; ++e) { const int d = half * 32 + i * 8 + e; vT[d * 136 + s] = f2bf(gelu_t(v[e]) * rs * ng[g * 64 + d]); } }
;   }
;   __syncthreads();
;   const bf16_t* W = (const bf16_t*)(P.ws + OFF_SGUW) + (size_t)((layer * 4 + g) * 128) * 128;
;   f32x4 acc[2][4] = {};
	v_mul_f32_e32 v8, v8, v12
	v_bfe_u32 v12, v8, 16, 1
	v_add3_u32 v8, v8, v12, s42
	ds_write_b16_d16_hi v24, v8 offset:6256
	v_mul_f32_e32 v8, 0x3d372713, v0
	v_mul_f32_e32 v8, v8, v0
	v_fma_f32 v8, v8, v0, v0
	v_mul_f32_e32 v8, 0x3f4c422a, v8
	v_mul_f32_e32 v8, -2.0, v8
	v_mul_f32_e32 v8, 0x3fb8aa3b, v8
	v_exp_f32_e32 v8, v8
	s_nop 0
	v_add_f32_e32 v8, 1.0, v8
	v_rcp_f32_e32 v8, v8
	s_nop 0
	v_mul_f32_e32 v0, v8, v0
	v_mul_f32_e32 v0, v31, v0
	v_mul_f32_e32 v0, v9, v0
	v_bfe_u32 v8, v0, 16, 1
	v_add3_u32 v0, v0, v8, s42
	ds_write_b16_d16_hi v24, v0 offset:6528
	v_mul_f32_e32 v0, 0x3d372713, v13
	v_mul_f32_e32 v0, v0, v13
	v_fma_f32 v0, v0, v13, v13
	v_mul_f32_e32 v0, 0x3f4c422a, v0
	v_mul_f32_e32 v0, -2.0, v0
	v_mul_f32_e32 v0, 0x3fb8aa3b, v0
	v_exp_f32_e32 v0, v0
	s_nop 0
	v_add_f32_e32 v0, 1.0, v0
	v_rcp_f32_e32 v0, v0
	s_nop 0
	v_mul_f32_e32 v0, v0, v13
	v_mul_f32_e32 v0, v31, v0
	v_mul_f32_e32 v0, v10, v0
	v_bfe_u32 v8, v0, 16, 1
	v_add3_u32 v0, v0, v8, s42
	ds_write_b16_d16_hi v24, v0 offset:6800
	v_mul_f32_e32 v0, 0x3d372713, v1
	v_mul_f32_e32 v0, v0, v1
	v_fma_f32 v0, v0, v1, v1
	v_mul_f32_e32 v0, 0x3f4c422a, v0
	v_mul_f32_e32 v0, -2.0, v0
	v_mul_f32_e32 v0, 0x3fb8aa3b, v0
	v_exp_f32_e32 v0, v0
	s_nop 0
	v_add_f32_e32 v0, 1.0, v0
	v_rcp_f32_e32 v0, v0
	s_nop 0
	v_mul_f32_e32 v0, v0, v1
	v_mul_f32_e32 v0, v31, v0
	v_mul_f32_e32 v0, v11, v0
	v_bfe_u32 v1, v0, 16, 1
	v_add3_u32 v0, v0, v1, s42
	ds_write_b16_d16_hi v24, v0 offset:7072
	v_mul_f32_e32 v0, 0x3d372713, v14
	v_mul_f32_e32 v0, v0, v14
	v_fma_f32 v0, v0, v14, v14
	v_mul_f32_e32 v0, 0x3f4c422a, v0
	v_mul_f32_e32 v0, -2.0, v0
	v_mul_f32_e32 v0, 0x3fb8aa3b, v0
	v_exp_f32_e32 v0, v0
	s_nop 0
	v_add_f32_e32 v0, 1.0, v0
	v_rcp_f32_e32 v0, v0
	s_nop 0
	v_mul_f32_e32 v0, v0, v14
	v_mul_f32_e32 v0, v31, v0
	v_mul_f32_e32 v0, v4, v0
	v_bfe_u32 v1, v0, 16, 1
	v_add3_u32 v0, v0, v1, s42
	ds_write_b16_d16_hi v24, v0 offset:7344
	v_mul_f32_e32 v0, 0x3d372713, v2
	v_mul_f32_e32 v0, v0, v2
	v_fma_f32 v0, v0, v2, v2
	v_mul_f32_e32 v0, 0x3f4c422a, v0
	v_mul_f32_e32 v0, -2.0, v0
	v_mul_f32_e32 v0, 0x3fb8aa3b, v0
	v_exp_f32_e32 v0, v0
	s_nop 0
	v_add_f32_e32 v0, 1.0, v0
	v_rcp_f32_e32 v0, v0
	s_nop 0
	v_mul_f32_e32 v0, v0, v2
	v_mul_f32_e32 v0, v31, v0
	v_mul_f32_e32 v0, v5, v0
	v_bfe_u32 v1, v0, 16, 1
	v_add3_u32 v0, v0, v1, s42
	ds_write_b16_d16_hi v24, v0 offset:7616
	v_mul_f32_e32 v0, 0x3d372713, v15
	v_mul_f32_e32 v0, v0, v15
	v_fma_f32 v0, v0, v15, v15
	v_mul_f32_e32 v0, 0x3f4c422a, v0
	v_mul_f32_e32 v0, -2.0, v0
	v_mul_f32_e32 v0, 0x3fb8aa3b, v0
	v_exp_f32_e32 v0, v0
	v_lshlrev_b32_e32 v2, 13, v33
	v_add_f32_e32 v0, 1.0, v0
	v_rcp_f32_e32 v0, v0
	s_nop 0
	v_mul_f32_e32 v0, v0, v15
	v_mul_f32_e32 v0, v31, v0
	v_mul_f32_e32 v0, v6, v0
	v_bfe_u32 v1, v0, 16, 1
	v_add3_u32 v0, v0, v1, s42
	ds_write_b16_d16_hi v24, v0 offset:7888
	v_mul_f32_e32 v0, 0x3d372713, v3
	v_mul_f32_e32 v0, v0, v3
	v_fma_f32 v0, v0, v3, v3
	v_mul_f32_e32 v0, 0x3f4c422a, v0
	v_mul_f32_e32 v0, -2.0, v0
	v_mul_f32_e32 v0, 0x3fb8aa3b, v0
	v_exp_f32_e32 v0, v0
	s_nop 0
	v_add_f32_e32 v0, 1.0, v0
	v_rcp_f32_e32 v0, v0
	s_nop 0
	v_mul_f32_e32 v0, v0, v3
	v_mul_f32_e32 v0, v31, v0
	v_mul_f32_e32 v0, v0, v7
	v_bfe_u32 v1, v0, 16, 1
	v_add3_u32 v0, v0, v1, s42
	ds_write_b16_d16_hi v24, v0 offset:8160
	v_mul_u32_u24_e32 v0, 0x110, v38
	v_lshlrev_b32_e32 v1, 4, v40
	v_add3_u32 v41, v60, v1, v0
	v_lshlrev_b32_e32 v0, 8, v38
	v_or3_b32 v0, v2, v0, v1
	v_mov_b32_e32 v1, v177
	v_lshl_add_u64 v[0:1], v[0:1], 0, v[176:177]
	v_mov_b32_e32 v24, 0
	v_lshl_add_u64 v[34:35], s[30:31], 0, v[0:1]
	s_mov_b64 s[30:31], 0
	v_mov_b32_e32 v25, v24
	v_mov_b32_e32 v26, v24
	v_mov_b32_e32 v27, v24
	v_mov_b32_e32 v28, v24
	v_mov_b32_e32 v29, v24
	v_mov_b32_e32 v30, v24
	v_mov_b32_e32 v31, v24
	v_mov_b32_e32 v20, v24
	v_mov_b32_e32 v21, v24
	v_mov_b32_e32 v22, v24
	v_mov_b32_e32 v23, v24
	v_mov_b32_e32 v16, v24
	v_mov_b32_e32 v17, v24
	v_mov_b32_e32 v18, v24
	v_mov_b32_e32 v19, v24
	v_mov_b32_e32 v12, v24
	v_mov_b32_e32 v13, v24
	v_mov_b32_e32 v14, v24
	v_mov_b32_e32 v15, v24
	v_mov_b32_e32 v8, v24
	v_mov_b32_e32 v9, v24
	v_mov_b32_e32 v10, v24
	v_mov_b32_e32 v11, v24
	v_mov_b32_e32 v4, v24
	v_mov_b32_e32 v5, v24
	v_mov_b32_e32 v6, v24
	v_mov_b32_e32 v7, v24
	v_mov_b32_e32 v0, v24
	v_mov_b32_e32 v1, v24
	v_mov_b32_e32 v2, v24
	v_mov_b32_e32 v3, v24
	s_waitcnt lgkmcnt(0)
	s_barrier
